# MLA: softmax scale/exp VALU rebalanced across the P.V MFMA gaps (shorter exposed tail)
# baseline (speedup 1.0000x reference)
; __device__ __forceinline__ unsigned pk4_fp8(float a, float b, float c, float d) { int p = __builtin_amdgcn_cvt_pk_fp8_f32(a, b, 0, false); p = __builtin_amdgcn_cvt_pk_fp8_f32(c, d, p, true); return (unsigned)p; }
; template <int MODE>
; __device__ __forceinline__ void partialSM(f32x16& p0, f32x16& p1, float& m_reg, float& mn, float& alpha, const float C, int kb, const float* btab, const bool nomask) {
;     ...
;     float pmax = p0[0];
; #pragma unroll
;     for (int r = 1; r < 16; ++r) pmax = fmaxf(pmax, p0[r]);
; #pragma unroll
;     for (int r = 0; r < 16; ++r) pmax = fmaxf(pmax, p1[r]);
;     { auto rr = __builtin_amdgcn_permlane32_swap(__float_as_uint(pmax), __float_as_uint(pmax), false, false); pmax = fmaxf(__uint_as_float(rr[0]), __uint_as_float(rr[1])); }
;     { const bool keep = __all((pmax - m_reg) * C <= (MODE == 0 ? 7.5f : 11.5f)); mn = keep ? m_reg : fmaxf(m_reg, pmax);   alpha = __builtin_amdgcn_exp2f((m_reg - mn) * C); m_reg = mn; }
;     const float mnC = -mn * C;
; __device__ __forceinline__ void finishSM8(f32x16& p0, f32x16& p1, float alpha, float& l_reg, bf16x8& pa0, bf16x8& pa1) {
; #pragma unroll
;   for (int r = 0; r < 16; ++r) p1[r] = __builtin_amdgcn_exp2f(p1[r]);
;   float ps = 0;
; #pragma unroll
;   for (int r = 0; r < 16; ++r) ps += p0[r];
; #pragma unroll
;   for (int r = 0; r < 16; ++r) ps += p1[r];
;   { auto rr = __builtin_amdgcn_permlane32_swap(__float_as_uint(ps), __float_as_uint(ps), false, false); ps = __uint_as_float(rr[0]) + __uint_as_float(rr[1]); }
;   l_reg = l_reg * alpha + ps;
;   const u32x4 w0 = {pk4_fp8(p0[0], p0[1], p0[2], p0[3]), pk4_fp8(p0[4], p0[5], p0[6], p0[7]), pk4_fp8(p0[8], p0[9], p0[10], p0[11]), pk4_fp8(p0[12], p0[13], p0[14], p0[15])};
;   const u32x4 w1 = {pk4_fp8(p1[0], p1[1], p1[2], p1[3]), pk4_fp8(p1[4], p1[5], p1[6], p1[7]), pk4_fp8(p1[8], p1[9], p1[10], p1[11]), pk4_fp8(p1[12], p1[13], p1[14], p1[15])};
;   pa0 = __builtin_bit_cast(bf16x8, w0); pa1 = __builtin_bit_cast(bf16x8, w1);
.LBB0_655:
	ds_read_b128 v[82:85], v231 offset:49152
	ds_read_b128 v[86:89], v231 offset:49168
	ds_read_b128 v[122:125], v231 offset:49216
	ds_read_b128 v[126:129], v231 offset:49232
	ds_read_b128 v[162:165], v231 offset:49280
	ds_read_b128 v[166:169], v231 offset:49296
	ds_read_b128 v[146:149], v231 offset:55808
	ds_read_b128 v[150:153], v231 offset:55824
	ds_read_b128 v[154:157], v231 offset:55872
	ds_read_b128 v[158:161], v231 offset:55888
	ds_read_b128 v[170:173], v231 offset:55936
	ds_read_b128 v[174:177], v231 offset:55952
	global_load_dwordx4 v[182:185], v[208:209], off
	global_load_dwordx4 v[186:189], v[206:207], off
	s_and_saveexec_b64 s[20:21], s[12:13]
	global_load_dwordx4 v[178:181], v[204:205], off
	s_or_b64 exec, exec, s[20:21]
	v_lshl_add_u64 v[206:207], v[206:207], 0, v[212:213]
	v_lshl_add_u64 v[204:205], v[204:205], 0, v[210:211]
	s_waitcnt lgkmcnt(10)
	v_mfma_scale_f32_32x32x64_f8f6f4 v[82:97], v[82:89], v[114:121], 0, v216, v216 op_sel_hi:[0,0,0]
	v_exp_f32_e32 v240, v98
	v_exp_f32_e32 v242, v99
	v_exp_f32_e32 v239, v100
	v_exp_f32_e32 v241, v101
	v_exp_f32_e32 v245, v102
	v_exp_f32_e32 v246, v103
	v_add_f32_e32 v0, 0, v66
	v_add_f32_e32 v0, v67, v0
	s_waitcnt lgkmcnt(8)
	v_mfma_scale_f32_32x32x64_f8f6f4 v[82:97], v[122:129], v[130:137], v[82:97], v216, v216 op_sel_hi:[0,0,0]
	v_exp_f32_e32 v243, v104
	v_exp_f32_e32 v244, v105
	v_exp_f32_e32 v247, v106
	v_exp_f32_e32 v250, v107
	v_exp_f32_e32 v248, v108
	v_exp_f32_e32 v249, v109
	v_add_f32_e32 v0, v68, v0
	v_add_f32_e32 v236, v242, v240
	v_add_f32_e32 v0, v69, v0
	v_add_f32_e32 v236, v239, v236
	v_add_f32_e32 v236, v241, v236
	s_waitcnt lgkmcnt(6)
	v_mfma_scale_f32_32x32x64_f8f6f4 v[82:97], v[162:169], v[138:145], v[82:97], v216, v216 op_sel_hi:[0,0,0]
	v_exp_f32_e32 v191, v110
	v_exp_f32_e32 v217, v111
	v_exp_f32_e32 v251, v112
	v_exp_f32_e32 v252, v113
	v_add_f32_e32 v0, v70, v0
	v_add_f32_e32 v236, v245, v236
	v_add_f32_e32 v0, v71, v0
	v_add_f32_e32 v236, v246, v236
	v_add_f32_e32 v0, v72, v0
	v_add_f32_e32 v236, v243, v236
	v_add_f32_e32 v0, v73, v0
	v_add_f32_e32 v236, v244, v236
	s_waitcnt lgkmcnt(4)
	v_mfma_scale_f32_32x32x64_f8f6f4 v[98:113], v[146:153], v[114:121], 0, v216, v216 op_sel_hi:[0,0,0]
	v_add_f32_e32 v0, v74, v0
	v_add_f32_e32 v236, v247, v236
	v_add_f32_e32 v0, v75, v0
	v_add_f32_e32 v236, v250, v236
	v_add_f32_e32 v0, v76, v0
	v_add_f32_e32 v236, v248, v236
	v_add_f32_e32 v0, v77, v0
	v_add_f32_e32 v236, v249, v236
	v_add_f32_e32 v0, v78, v0
	v_add_f32_e32 v236, v191, v236
	s_waitcnt lgkmcnt(2)
	v_mfma_scale_f32_32x32x64_f8f6f4 v[98:113], v[154:161], v[130:137], v[98:113], v216, v216 op_sel_hi:[0,0,0]
	v_add_f32_e32 v0, v79, v0
	v_add_f32_e32 v236, v217, v236
	v_add_f32_e32 v0, v80, v0
	v_add_f32_e32 v236, v251, v236
	v_add_f32_e32 v0, v81, v0
	v_add_f32_e32 v236, v252, v236
	v_add_f32_e32 v235, v236, v0
	v_mov_b32_e32 v236, v235
	s_waitcnt lgkmcnt(0)
	v_mfma_scale_f32_32x32x64_f8f6f4 v[98:113], v[170:177], v[138:145], v[98:113], v216, v216 op_sel_hi:[0,0,0]
	s_nop 0
	v_permlane32_swap_b32_e32 v235, v236
	ds_read_b128 v[154:157], v230
	ds_read_b128 v[158:161], v230 offset:16
	ds_read_b128 v[146:149], v230 offset:2560
	ds_read_b128 v[150:153], v230 offset:2576
	ds_read_b128 v[122:125], v230 offset:5120
	ds_read_b128 v[126:129], v230 offset:5136
	ds_read_b128 v[166:169], v230 offset:7696
	v_cvt_pk_fp8_f32 v170, v66, v67
	v_cvt_pk_fp8_f32 v171, v70, v71
	v_cvt_pk_fp8_f32 v172, v74, v75
	v_cvt_pk_fp8_f32 v173, v78, v79
	v_cvt_pk_fp8_f32 v174, v240, v242
	v_cvt_pk_fp8_f32 v175, v245, v246
	v_cvt_pk_fp8_f32 v176, v247, v250
	v_cvt_pk_fp8_f32 v177, v191, v217
	v_cvt_pk_fp8_f32 v170, v68, v69 op_sel:[0,0,1]
	v_cvt_pk_fp8_f32 v171, v72, v73 op_sel:[0,0,1]
	v_cvt_pk_fp8_f32 v172, v76, v77 op_sel:[0,0,1]
	v_cvt_pk_fp8_f32 v173, v80, v81 op_sel:[0,0,1]
	v_cvt_pk_fp8_f32 v174, v239, v241 op_sel:[0,0,1]
	v_cvt_pk_fp8_f32 v175, v243, v244 op_sel:[0,0,1]
	v_cvt_pk_fp8_f32 v176, v248, v249 op_sel:[0,0,1]
	v_cvt_pk_fp8_f32 v177, v251, v252 op_sel:[0,0,1]
	v_max_f32_e32 v0, v83, v83
	v_max_f32_e32 v163, v98, v98
	v_max_f32_e32 v162, v82, v82
	v_max3_f32 v163, v163, v99, v100
	v_max_f32_e32 v0, v162, v0
	v_max3_f32 v163, v163, v101, v102
	v_max3_f32 v0, v0, v84, v85
	v_max3_f32 v163, v163, v103, v104
	v_max3_f32 v0, v0, v86, v87
	v_max3_f32 v163, v163, v105, v106
	v_max3_f32 v0, v0, v88, v89
	v_max3_f32 v163, v163, v107, v108
	v_max3_f32 v0, v0, v90, v91
	v_max3_f32 v163, v163, v109, v110
	v_max3_f32 v0, v0, v92, v93
	v_max3_f32 v163, v163, v111, v112
	v_max3_f32 v0, v0, v94, v95
	v_max_f32_e32 v163, v163, v113
	v_max3_f32 v0, v0, v96, v97
	v_max_f32_e32 v0, v0, v163
	v_mov_b32_e32 v162, v0
	s_nop 1
	v_permlane32_swap_b32_e32 v0, v162
	v_max_f32_e32 v162, v162, v162
	v_max_f32_e32 v0, v0, v0
	v_max_f32_e32 v0, v0, v162
	v_sub_f32_e32 v162, v0, v237
	v_mul_f32_e32 v162, 0x3dd53b94, v162
	v_cmp_ge_f32_e32 vcc, s57, v162
	s_cmp_eq_u64 vcc, exec
	v_max_f32_e32 v162, v237, v237
	s_cselect_b64 vcc, -1, 0
	v_max_f32_e32 v0, v162, v0
	v_cndmask_b32_e32 v238, v0, v237, vcc
	v_sub_f32_e32 v0, v237, v238
	v_mul_f32_e32 v0, 0x3dd53b94, v0
	v_exp_f32_e32 v0, v0
	ds_read_b128 v[162:165], v230 offset:7680
	s_waitcnt lgkmcnt(0)
; template <int MODE>
; __device__ __forceinline__ void partialSM(f32x16& p0, f32x16& p1, float& m_reg, float& mn, float& alpha, const float C, int kb, const float* btab, const bool nomask) {
;     ...
;     const float mnC = -mn * C;
; #pragma unroll
;     for (int r = 0; r < 16; ++r) p0[r] = fmaf(p0[r], C, mnC);
; #pragma unroll
;     for (int r = 0; r < 16; ++r) p1[r] = fmaf(p1[r], C, mnC);
; #pragma unroll
;     for (int r = 0; r < 16; ++r) p0[r] = __builtin_amdgcn_exp2f(p0[r]);
	v_mul_f32_e32 v66, 0xbdd53b94, v238
	v_cmp_gt_f32_e32 vcc, 1.0, v0
	s_nop 0
	v_mfma_scale_f32_32x32x64_f8f6f4 v[50:65], v[170:177], v[154:161], v[50:65], v216, v216 op_sel_hi:[0,0,0]
	v_fmamk_f32 v82, v82, 0x3dd53b94, v66
	v_fmamk_f32 v83, v83, 0x3dd53b94, v66
	v_fmamk_f32 v84, v84, 0x3dd53b94, v66
	v_fmamk_f32 v85, v85, 0x3dd53b94, v66
	v_fmamk_f32 v86, v86, 0x3dd53b94, v66
	v_fmamk_f32 v87, v87, 0x3dd53b94, v66
	v_exp_f32_e32 v82, v82
	v_exp_f32_e32 v83, v83
	v_exp_f32_e32 v84, v84
	v_exp_f32_e32 v85, v85
	v_exp_f32_e32 v86, v86
	v_exp_f32_e32 v87, v87
	v_mfma_scale_f32_32x32x64_f8f6f4 v[34:49], v[170:177], v[146:153], v[34:49], v216, v216 op_sel_hi:[0,0,0]
	v_fmamk_f32 v88, v88, 0x3dd53b94, v66
	v_fmamk_f32 v89, v89, 0x3dd53b94, v66
	v_fmamk_f32 v90, v90, 0x3dd53b94, v66
	v_fmamk_f32 v91, v91, 0x3dd53b94, v66
	v_fmamk_f32 v92, v92, 0x3dd53b94, v66
	v_exp_f32_e32 v88, v88
	v_exp_f32_e32 v89, v89
	v_exp_f32_e32 v90, v90
	v_exp_f32_e32 v91, v91
	v_exp_f32_e32 v92, v92
	v_pk_fma_f32 v[98:99], v[98:99], s[78:79], v[66:67] op_sel_hi:[1,0,0]
	v_pk_fma_f32 v[100:101], v[100:101], s[78:79], v[66:67] op_sel_hi:[1,0,0]
	v_mfma_scale_f32_32x32x64_f8f6f4 v[18:33], v[170:177], v[122:129], v[18:33], v216, v216 op_sel_hi:[0,0,0]
	v_fmamk_f32 v93, v93, 0x3dd53b94, v66
	v_fmamk_f32 v94, v94, 0x3dd53b94, v66
	v_fmamk_f32 v95, v95, 0x3dd53b94, v66
	v_fmamk_f32 v96, v96, 0x3dd53b94, v66
	v_fmamk_f32 v97, v97, 0x3dd53b94, v66
	v_exp_f32_e32 v93, v93
	v_exp_f32_e32 v94, v94
	v_exp_f32_e32 v95, v95
	v_exp_f32_e32 v96, v96
	v_exp_f32_e32 v97, v97
	v_pk_fma_f32 v[102:103], v[102:103], s[78:79], v[66:67] op_sel_hi:[1,0,0]
	v_pk_fma_f32 v[104:105], v[104:105], s[78:79], v[66:67] op_sel_hi:[1,0,0]
	v_mfma_scale_f32_32x32x64_f8f6f4 v[2:17], v[170:177], v[162:169], v[2:17], v216, v216 op_sel_hi:[0,0,0]
	v_pk_fma_f32 v[106:107], v[106:107], s[78:79], v[66:67] op_sel_hi:[1,0,0]
	v_pk_fma_f32 v[108:109], v[108:109], s[78:79], v[66:67] op_sel_hi:[1,0,0]
	v_pk_fma_f32 v[110:111], v[110:111], s[78:79], v[66:67] op_sel_hi:[1,0,0]
	v_pk_fma_f32 v[112:113], v[112:113], s[78:79], v[66:67] op_sel_hi:[1,0,0]
	s_cbranch_vccz .LBB0_671
	s_and_saveexec_b64 s[20:21], s[8:9]
	ds_write_b32 v229, v0 offset:128
	s_or_b64 exec, exec, s[20:21]
	s_waitcnt lgkmcnt(0)
	ds_read_b128 v[66:69], v228 offset:224
	ds_read_b128 v[70:73], v228 offset:192
	ds_read_b128 v[74:77], v228 offset:160
	ds_read_b128 v[78:81], v228 offset:128
	s_waitcnt lgkmcnt(3)
	s_nop 7
	v_pk_mul_f32 v[64:65], v[64:65], v[68:69]
	s_waitcnt lgkmcnt(2)
	v_pk_mul_f32 v[60:61], v[60:61], v[72:73]
	s_waitcnt lgkmcnt(1)
	v_pk_mul_f32 v[56:57], v[56:57], v[76:77]
	s_waitcnt lgkmcnt(0)
	v_pk_mul_f32 v[52:53], v[52:53], v[80:81]
	v_pk_mul_f32 v[62:63], v[62:63], v[66:67]
	v_pk_mul_f32 v[58:59], v[58:59], v[70:71]
	v_pk_mul_f32 v[54:55], v[54:55], v[74:75]
	v_pk_mul_f32 v[50:51], v[50:51], v[78:79]
	v_pk_mul_f32 v[48:49], v[48:49], v[68:69]
	v_pk_mul_f32 v[44:45], v[44:45], v[72:73]
	v_pk_mul_f32 v[40:41], v[40:41], v[76:77]
	v_pk_mul_f32 v[36:37], v[36:37], v[80:81]
	v_pk_mul_f32 v[46:47], v[46:47], v[66:67]
	v_pk_mul_f32 v[42:43], v[42:43], v[70:71]
	v_pk_mul_f32 v[38:39], v[38:39], v[74:75]
	v_pk_mul_f32 v[34:35], v[34:35], v[78:79]
	v_pk_mul_f32 v[32:33], v[32:33], v[68:69]
	v_pk_mul_f32 v[28:29], v[28:29], v[72:73]
	v_pk_mul_f32 v[24:25], v[24:25], v[76:77]
	v_pk_mul_f32 v[20:21], v[20:21], v[80:81]
	v_pk_mul_f32 v[30:31], v[30:31], v[66:67]
	v_pk_mul_f32 v[26:27], v[26:27], v[70:71]
	v_pk_mul_f32 v[22:23], v[22:23], v[74:75]
	v_pk_mul_f32 v[18:19], v[18:19], v[78:79]
	v_pk_mul_f32 v[16:17], v[16:17], v[68:69]
	v_pk_mul_f32 v[12:13], v[12:13], v[72:73]
	v_pk_mul_f32 v[8:9], v[8:9], v[76:77]
	v_pk_mul_f32 v[4:5], v[4:5], v[80:81]
	v_pk_mul_f32 v[14:15], v[14:15], v[66:67]
	v_pk_mul_f32 v[10:11], v[10:11], v[70:71]
	v_pk_mul_f32 v[6:7], v[6:7], v[74:75]
	v_pk_mul_f32 v[2:3], v[2:3], v[78:79]
.LBB0_671:
	s_waitcnt vmcnt(0)
	s_waitcnt vmcnt(1)
	ds_write_b128 v225, v[182:185]
	s_waitcnt vmcnt(0)
	ds_write_b128 v226, v[186:189] offset:32768
	s_and_saveexec_b64 s[20:21], s[12:13]
	ds_write_b128 v234, v[178:181] offset:32768
	s_or_b64 exec, exec, s[20:21]
	s_lshl_b32 s26, s25, 6
	s_waitcnt lgkmcnt(0)
	s_barrier
	ds_read_b128 v[66:69], v231 offset:32768
	ds_read_b128 v[70:73], v231 offset:32784
	ds_read_b128 v[122:125], v231 offset:32832
	ds_read_b128 v[126:129], v231 offset:32848
	ds_read_b128 v[162:165], v231 offset:32896
	ds_read_b128 v[166:169], v231 offset:32912
	ds_read_b128 v[146:149], v231 offset:39424
	ds_read_b128 v[150:153], v231 offset:39440
	ds_read_b128 v[154:157], v231 offset:39488
	ds_read_b128 v[158:161], v231 offset:39504
	ds_read_b128 v[170:173], v231 offset:39552
	ds_read_b128 v[174:177], v231 offset:39568
	global_load_dwordx4 v[182:185], v[208:209], off offset:64
	global_load_dwordx4 v[186:189], v[206:207], off
	s_and_saveexec_b64 s[20:21], s[12:13]
	global_load_dwordx4 v[178:181], v[204:205], off
	s_or_b64 exec, exec, s[20:21]
	v_lshl_add_u64 v[206:207], v[206:207], 0, v[212:213]
	v_lshl_add_u64 v[204:205], v[204:205], 0, v[210:211]
	s_waitcnt lgkmcnt(10)
	v_mfma_scale_f32_32x32x64_f8f6f4 v[66:81], v[66:73], v[114:121], 0, v216, v216 op_sel_hi:[0,0,0]
	v_exp_f32_e32 v243, v98
	v_exp_f32_e32 v244, v99
	v_exp_f32_e32 v241, v100
	v_exp_f32_e32 v242, v101
	v_exp_f32_e32 v247, v102
	v_exp_f32_e32 v248, v103
	v_add_f32_e32 v239, 0, v82
	v_add_f32_e32 v239, v83, v239
	s_waitcnt lgkmcnt(8)
	v_mfma_scale_f32_32x32x64_f8f6f4 v[66:81], v[122:129], v[130:137], v[66:81], v216, v216 op_sel_hi:[0,0,0]
	v_exp_f32_e32 v245, v104
	v_exp_f32_e32 v246, v105
	v_exp_f32_e32 v249, v106
	v_exp_f32_e32 v252, v107
	v_exp_f32_e32 v250, v108
	v_exp_f32_e32 v251, v109
	v_add_f32_e32 v239, v84, v239
	v_add_f32_e32 v240, v244, v243
	v_add_f32_e32 v239, v85, v239
	v_add_f32_e32 v240, v241, v240
	v_add_f32_e32 v240, v242, v240
	s_waitcnt lgkmcnt(6)
; __device__ __forceinline__ unsigned pk4_fp8(float a, float b, float c, float d) { int p = __builtin_amdgcn_cvt_pk_fp8_f32(a, b, 0, false); p = __builtin_amdgcn_cvt_pk_fp8_f32(c, d, p, true); return (unsigned)p; }
; template <int MODE>
; __device__ __forceinline__ void partialSM(f32x16& p0, f32x16& p1, float& m_reg, float& mn, float& alpha, const float C, int kb, const float* btab, const bool nomask) {
;     ...
;     float pmax = p0[0];
; #pragma unroll
;     for (int r = 1; r < 16; ++r) pmax = fmaxf(pmax, p0[r]);
; #pragma unroll
;     for (int r = 0; r < 16; ++r) pmax = fmaxf(pmax, p1[r]);
;     { auto rr = __builtin_amdgcn_permlane32_swap(__float_as_uint(pmax), __float_as_uint(pmax), false, false); pmax = fmaxf(__uint_as_float(rr[0]), __uint_as_float(rr[1])); }
;     { const bool keep = __all((pmax - m_reg) * C <= (MODE == 0 ? 7.5f : 11.5f)); mn = keep ? m_reg : fmaxf(m_reg, pmax);   alpha = __builtin_amdgcn_exp2f((m_reg - mn) * C); m_reg = mn; }
;     const float mnC = -mn * C;
; #pragma unroll
;     for (int r = 0; r < 16; ++r) p0[r] = fmaf(p0[r], C, mnC);
; #pragma unroll
;     for (int r = 0; r < 16; ++r) p1[r] = fmaf(p1[r], C, mnC);
; #pragma unroll
;     for (int r = 0; r < 16; ++r) p0[r] = __builtin_amdgcn_exp2f(p0[r]);
; __device__ __forceinline__ void finishSM8(f32x16& p0, f32x16& p1, float alpha, float& l_reg, bf16x8& pa0, bf16x8& pa1) {
; #pragma unroll
;   for (int r = 0; r < 16; ++r) p1[r] = __builtin_amdgcn_exp2f(p1[r]);
;   float ps = 0;
; #pragma unroll
;   for (int r = 0; r < 16; ++r) ps += p0[r];
; #pragma unroll
;   for (int r = 0; r < 16; ++r) ps += p1[r];
;   { auto rr = __builtin_amdgcn_permlane32_swap(__float_as_uint(ps), __float_as_uint(ps), false, false); ps = __uint_as_float(rr[0]) + __uint_as_float(rr[1]); }
;   l_reg = l_reg * alpha + ps;
;   const u32x4 w0 = {pk4_fp8(p0[0], p0[1], p0[2], p0[3]), pk4_fp8(p0[4], p0[5], p0[6], p0[7]), pk4_fp8(p0[8], p0[9], p0[10], p0[11]), pk4_fp8(p0[12], p0[13], p0[14], p0[15])};
;   const u32x4 w1 = {pk4_fp8(p1[0], p1[1], p1[2], p1[3]), pk4_fp8(p1[4], p1[5], p1[6], p1[7]), pk4_fp8(p1[8], p1[9], p1[10], p1[11]), pk4_fp8(p1[12], p1[13], p1[14], p1[15])};
;   pa0 = __builtin_bit_cast(bf16x8, w0); pa1 = __builtin_bit_cast(bf16x8, w1);
	v_mfma_scale_f32_32x32x64_f8f6f4 v[66:81], v[162:169], v[138:145], v[66:81], v216, v216 op_sel_hi:[0,0,0]
	v_exp_f32_e32 v254, v110
	v_exp_f32_e32 v191, v111
	v_exp_f32_e32 v253, v112
	v_exp_f32_e32 v217, v113
	v_add_f32_e32 v239, v86, v239
	v_add_f32_e32 v240, v247, v240
	v_add_f32_e32 v239, v87, v239
	v_add_f32_e32 v240, v248, v240
	v_add_f32_e32 v239, v88, v239
	v_add_f32_e32 v240, v245, v240
	v_add_f32_e32 v239, v89, v239
	v_add_f32_e32 v240, v246, v240
	s_waitcnt lgkmcnt(4)
	v_mfma_scale_f32_32x32x64_f8f6f4 v[98:113], v[146:153], v[114:121], 0, v216, v216 op_sel_hi:[0,0,0]
	v_add_f32_e32 v239, v90, v239
	v_add_f32_e32 v240, v249, v240
	v_add_f32_e32 v239, v91, v239
	v_add_f32_e32 v240, v252, v240
	v_add_f32_e32 v239, v92, v239
	v_add_f32_e32 v240, v250, v240
	v_add_f32_e32 v239, v93, v239
	v_add_f32_e32 v240, v251, v240
	v_add_f32_e32 v239, v94, v239
	v_add_f32_e32 v240, v254, v240
	s_waitcnt lgkmcnt(2)
	v_mfma_scale_f32_32x32x64_f8f6f4 v[98:113], v[154:161], v[130:137], v[98:113], v216, v216 op_sel_hi:[0,0,0]
	v_add_f32_e32 v239, v95, v239
	v_add_f32_e32 v240, v191, v240
	v_add_f32_e32 v239, v96, v239
	v_add_f32_e32 v240, v253, v240
	v_add_f32_e32 v239, v97, v239
	v_add_f32_e32 v240, v217, v240
	v_add_f32_e32 v239, v240, v239
	v_mov_b32_e32 v240, v239
	s_waitcnt lgkmcnt(0)
	v_mfma_scale_f32_32x32x64_f8f6f4 v[98:113], v[170:177], v[138:145], v[98:113], v216, v216 op_sel_hi:[0,0,0]
	s_nop 0
	v_permlane32_swap_b32_e32 v239, v240
	ds_read_b128 v[154:157], v230 offset:18432
	ds_read_b128 v[158:161], v230 offset:18448
	ds_read_b128 v[146:149], v230 offset:20992
	ds_read_b128 v[150:153], v230 offset:21008
	ds_read_b128 v[122:125], v230 offset:23552
	ds_read_b128 v[126:129], v230 offset:23568
	ds_read_b128 v[166:169], v230 offset:26128
	v_cvt_pk_fp8_f32 v82, v82, v83
	v_cvt_pk_fp8_f32 v83, v86, v87
	v_cvt_pk_fp8_f32 v82, v84, v85 op_sel:[0,0,1]
	v_cvt_pk_fp8_f32 v83, v88, v89 op_sel:[0,0,1]
	v_cvt_pk_fp8_f32 v84, v90, v91
	v_cvt_pk_fp8_f32 v85, v94, v95
	v_cvt_pk_fp8_f32 v84, v92, v93 op_sel:[0,0,1]
	v_cvt_pk_fp8_f32 v85, v96, v97 op_sel:[0,0,1]
	v_cvt_pk_fp8_f32 v86, v243, v244
	v_cvt_pk_fp8_f32 v87, v247, v248
	v_cvt_pk_fp8_f32 v86, v241, v242 op_sel:[0,0,1]
	v_cvt_pk_fp8_f32 v87, v245, v246 op_sel:[0,0,1]
	v_cvt_pk_fp8_f32 v88, v249, v252
	v_cvt_pk_fp8_f32 v89, v254, v191
	v_cvt_pk_fp8_f32 v88, v250, v251 op_sel:[0,0,1]
	v_cvt_pk_fp8_f32 v89, v253, v217 op_sel:[0,0,1]
	v_max_f32_e32 v162, v67, v67
	v_max_f32_e32 v164, v98, v98
	v_max_f32_e32 v163, v66, v66
	v_max3_f32 v164, v164, v99, v100
	v_max_f32_e32 v162, v163, v162
	v_max3_f32 v164, v164, v101, v102
	v_max3_f32 v162, v162, v68, v69
	v_max3_f32 v164, v164, v103, v104
	v_max3_f32 v162, v162, v70, v71
	v_max3_f32 v164, v164, v105, v106
	v_max3_f32 v162, v162, v72, v73
	v_max3_f32 v164, v164, v107, v108
	v_max3_f32 v162, v162, v74, v75
	v_max3_f32 v164, v164, v109, v110
	v_max3_f32 v162, v162, v76, v77
	v_max3_f32 v164, v164, v111, v112
	v_max3_f32 v162, v162, v78, v79
	v_max_f32_e32 v164, v164, v113
	v_max3_f32 v162, v162, v80, v81
	v_max_f32_e32 v162, v162, v164
	v_mov_b32_e32 v163, v162
	s_nop 1
	v_permlane32_swap_b32_e32 v162, v163
	v_max_f32_e32 v163, v163, v163
	v_max_f32_e32 v162, v162, v162
	v_max_f32_e32 v162, v162, v163
	v_sub_f32_e32 v163, v162, v238
	v_mul_f32_e32 v163, 0x3dd53b94, v163
	v_cmp_ge_f32_e32 vcc, s57, v163
	s_cmp_eq_u64 vcc, exec
	v_max_f32_e32 v163, v238, v238
	s_cselect_b64 vcc, -1, 0
	v_max_f32_e32 v162, v163, v162
	v_cndmask_b32_e32 v237, v162, v238, vcc
	v_sub_f32_e32 v170, v238, v237
	v_mul_f32_e32 v170, 0x3dd53b94, v170
	v_exp_f32_e32 v170, v170
	ds_read_b128 v[162:165], v230 offset:26112
	s_waitcnt lgkmcnt(0)
	v_mul_f32_e32 v172, 0xbdd53b94, v237
	v_cmp_gt_f32_e32 vcc, 1.0, v170
	s_nop 0
	v_mfma_scale_f32_32x32x64_f8f6f4 v[50:65], v[82:89], v[154:161], v[50:65], v216, v216 op_sel_hi:[0,0,0]
	v_fmamk_f32 v66, v66, 0x3dd53b94, v172
	v_fmamk_f32 v67, v67, 0x3dd53b94, v172
	v_fmamk_f32 v68, v68, 0x3dd53b94, v172
	v_fmamk_f32 v69, v69, 0x3dd53b94, v172
	v_fmamk_f32 v70, v70, 0x3dd53b94, v172
	v_fmamk_f32 v71, v71, 0x3dd53b94, v172
	v_exp_f32_e32 v66, v66
	v_exp_f32_e32 v67, v67
	v_exp_f32_e32 v68, v68
	v_exp_f32_e32 v69, v69
	v_exp_f32_e32 v70, v70
	v_exp_f32_e32 v71, v71
	v_mfma_scale_f32_32x32x64_f8f6f4 v[34:49], v[82:89], v[146:153], v[34:49], v216, v216 op_sel_hi:[0,0,0]
	v_fmamk_f32 v72, v72, 0x3dd53b94, v172
	v_fmamk_f32 v73, v73, 0x3dd53b94, v172
	v_fmamk_f32 v74, v74, 0x3dd53b94, v172
	v_fmamk_f32 v75, v75, 0x3dd53b94, v172
	v_fmamk_f32 v76, v76, 0x3dd53b94, v172
	v_exp_f32_e32 v72, v72
	v_exp_f32_e32 v73, v73
	v_exp_f32_e32 v74, v74
	v_exp_f32_e32 v75, v75
	v_exp_f32_e32 v76, v76
	v_pk_fma_f32 v[98:99], v[98:99], s[78:79], v[172:173] op_sel_hi:[1,0,0]
	v_pk_fma_f32 v[100:101], v[100:101], s[78:79], v[172:173] op_sel_hi:[1,0,0]
	v_mfma_scale_f32_32x32x64_f8f6f4 v[18:33], v[82:89], v[122:129], v[18:33], v216, v216 op_sel_hi:[0,0,0]
	v_fmamk_f32 v77, v77, 0x3dd53b94, v172
	v_fmamk_f32 v78, v78, 0x3dd53b94, v172
	v_fmamk_f32 v79, v79, 0x3dd53b94, v172
	v_fmamk_f32 v80, v80, 0x3dd53b94, v172
	v_fmamk_f32 v81, v81, 0x3dd53b94, v172
	v_exp_f32_e32 v77, v77
	v_exp_f32_e32 v78, v78
	v_exp_f32_e32 v79, v79
	v_exp_f32_e32 v80, v80
	v_exp_f32_e32 v81, v81
	v_pk_fma_f32 v[102:103], v[102:103], s[78:79], v[172:173] op_sel_hi:[1,0,0]
	v_pk_fma_f32 v[104:105], v[104:105], s[78:79], v[172:173] op_sel_hi:[1,0,0]
	v_mfma_scale_f32_32x32x64_f8f6f4 v[2:17], v[82:89], v[162:169], v[2:17], v216, v216 op_sel_hi:[0,0,0]
	v_pk_fma_f32 v[106:107], v[106:107], s[78:79], v[172:173] op_sel_hi:[1,0,0]
	v_pk_fma_f32 v[108:109], v[108:109], s[78:79], v[172:173] op_sel_hi:[1,0,0]
	v_pk_fma_f32 v[110:111], v[110:111], s[78:79], v[172:173] op_sel_hi:[1,0,0]
	v_pk_fma_f32 v[112:113], v[112:113], s[78:79], v[172:173] op_sel_hi:[1,0,0]
	s_cbranch_vccz .LBB0_654
	s_and_saveexec_b64 s[20:21], s[8:9]
	s_cbranch_execz .LBB0_653
	ds_write_b32 v229, v170 offset:128
	s_branch .LBB0_653
